# v21 + the upper-half copy of the split sample mixer no longer drains the pooling stores (leftover vmcnt(0) waits) before issuing its first map loads
# baseline (speedup 1.0000x reference)
; #define LAS __attribute__((address_space(3)))
; __device__ __forceinline__ float dot4(f32x4 a, f32x4 b) { return (a[0] * b[0] + a[1] * b[1]) + (a[2] * b[2] + a[3] * b[3]); }
; __device__ __forceinline__ void unpack8(u32x4 w, f32x4& a, f32x4& b) { a = (f32x4){bflo(w.x), bfhi(w.x), bflo(w.y), bfhi(w.y)}; b = (f32x4){bflo(w.z), bfhi(w.z), bflo(w.w), bfhi(w.w)}; }
; __device__ __forceinline__ void sample_mix_even(Frame& F0, int j, int b) {
;     ...
;     __syncthreads();
;     float tot = 0.f;
; #pragma unroll
;     for (int i = 0; i < 8; ++i) tot += red[i];
;     const float rv = rsqrtf(tot * (1.0f / D) + EPS);
; #pragma unroll
;     for (int k = 0; k < 2; ++k) {
;         const int d = tid + 512 * k, g = d >> 8, dd = d & 255;
;         const bf16_t* pm = ((bf16_t*)(F.ws + WS_PMT)) + (size_t)(j * 4 + g) * 65536 + (size_t)dd * 256; const LAS float* pg = pl + g * 256;
;         float a = 0.f;
; #pragma unroll
;         for (int hb = 0; hb < 2; ++hb) {
;             u32x4 pr[16];
; #pragma unroll
;             for (int i = 0; i < 16; ++i) pr[i] = *(const u32x4*)(pm + hb * 128 + i * 8);
; #pragma unroll
;             for (int i = 0; i < 16; ++i) { f32x4 p0, p1; unpack8(pr[i], p0, p1); const LAS float* q = pg + hb * 128 + i * 8; a += dot4(p0, *(const LAS f32x4*)q) + dot4(p1, *(const LAS f32x4*)(q + 4)); }
.Lsmx_hi:
	ds_read_b128 v[0:3], v201 offset:4096
	ds_read_b128 v[4:7], v201 offset:4112
	s_mov_b32 s4, 0x800000
	s_waitcnt lgkmcnt(1)
	v_add_f32_e32 v0, 0, v0
	v_add_f32_e32 v0, v0, v1
	v_add_f32_e32 v0, v0, v2
	v_add_f32_e32 v0, v0, v3
	s_waitcnt lgkmcnt(0)
	v_add_f32_e32 v0, v0, v4
	v_add_f32_e32 v0, v0, v5
	v_add_f32_e32 v0, v0, v6
	v_add_f32_e32 v0, v0, v7
	v_mov_b32_e32 v1, 0x358637bd
	v_fmamk_f32 v0, v0, 0x3a800000, v1
	v_cmp_gt_f32_e32 vcc, s4, v0
	v_mul_f32_e32 v1, 0x4b800000, v0
	s_load_dwordx8 s[4:11], s[14:15], 0x60
	v_cndmask_b32_e32 v0, v0, v1, vcc
	v_rsq_f32_e32 v0, v0
	s_lshl_b64 s[14:15], s[16:17], 12
	s_add_u32 s2, s2, s14
	s_addc_u32 s3, s3, s15
	v_mul_f32_e32 v1, 0x45800000, v0
	v_cndmask_b32_e32 v59, v0, v1, vcc
	s_lshl_b64 s[0:1], s[0:1], 12
	s_add_u32 s0, s12, s0
	s_addc_u32 s1, s13, s1
	s_add_i32 s93, s93, s22
	s_cmp_lt_i32 s93, 16
	s_waitcnt lgkmcnt(0)
	s_waitcnt lgkmcnt(0)
	s_waitcnt lgkmcnt(0)
	s_waitcnt lgkmcnt(0)
	s_waitcnt lgkmcnt(0)
	s_waitcnt lgkmcnt(0)
	s_waitcnt lgkmcnt(0)
	s_waitcnt lgkmcnt(0)
	s_waitcnt lgkmcnt(0)
	s_waitcnt lgkmcnt(0)
	s_waitcnt lgkmcnt(0)
	s_waitcnt lgkmcnt(0)
	s_waitcnt lgkmcnt(0)
	s_waitcnt lgkmcnt(0)
	s_waitcnt lgkmcnt(0)
	s_waitcnt lgkmcnt(0)
	s_waitcnt lgkmcnt(0)
	s_waitcnt lgkmcnt(0)
	s_waitcnt lgkmcnt(0)
	s_waitcnt lgkmcnt(0)
	s_waitcnt lgkmcnt(0)
	s_waitcnt lgkmcnt(0)
	s_waitcnt lgkmcnt(0)
	s_waitcnt lgkmcnt(0)
	s_waitcnt lgkmcnt(0)
	s_waitcnt lgkmcnt(0)
	s_waitcnt lgkmcnt(0)
	s_waitcnt lgkmcnt(0)
	s_waitcnt lgkmcnt(0)
	s_waitcnt lgkmcnt(0)
	s_waitcnt lgkmcnt(0)
	s_waitcnt lgkmcnt(0)
	s_waitcnt lgkmcnt(0)
	s_waitcnt lgkmcnt(0)
	s_waitcnt lgkmcnt(0)
	s_waitcnt lgkmcnt(0)
	s_waitcnt lgkmcnt(0)
	s_waitcnt lgkmcnt(0)
	s_waitcnt lgkmcnt(0)
	s_waitcnt lgkmcnt(0)
	s_waitcnt lgkmcnt(0)
	s_waitcnt lgkmcnt(0)
	s_waitcnt lgkmcnt(0)
	s_waitcnt lgkmcnt(0)
	s_waitcnt lgkmcnt(0)
	s_waitcnt lgkmcnt(0)
	s_waitcnt lgkmcnt(0)
	s_waitcnt lgkmcnt(0)
	v_add_u32_e32 v28, s90, v48
	v_ashrrev_i32_e32 v29, 31, v28
	v_lshlrev_b64 v[30:31], 2, v[28:29]
	v_lshl_add_u64 v[28:29], s[10:11], 0, v[30:31]
	v_lshl_add_u64 v[30:31], s[4:5], 0, v[30:31]
	s_waitcnt lgkmcnt(0)
	s_waitcnt lgkmcnt(0)
	s_waitcnt lgkmcnt(0)
	s_waitcnt lgkmcnt(0)
	s_waitcnt lgkmcnt(0)
	s_waitcnt lgkmcnt(0)
	s_waitcnt lgkmcnt(0)
	s_nop 0
	v_lshl_add_u64 v[12:13], v[48:49], 2, s[2:3]
	s_mov_b32 s2, 0x54b0000
	s_nop 0
	s_nop 0
	s_waitcnt lgkmcnt(0)
	s_waitcnt lgkmcnt(0)
	s_waitcnt lgkmcnt(0)
	s_waitcnt lgkmcnt(0)
	s_waitcnt lgkmcnt(0)
	s_waitcnt lgkmcnt(0)
	v_add_u32_e32 v22, s24, v62
	v_lshl_add_u64 v[0:1], v[48:49], 1, s[0:1]
	s_mov_b64 s[0:1], 0x1b500000
	v_lshl_add_u64 v[20:21], v[0:1], 0, s[0:1]
	s_mov_b32 s0, 0x1b500000
	v_ashrrev_i32_e32 v23, 31, v22
	s_nop 0
	v_lshlrev_b64 v[0:1], 17, v[22:23]
	v_lshl_add_u64 v[32:33], v[52:53], 0, v[0:1]
	global_load_dwordx4 v[36:39], v[32:33], off
	global_load_dwordx4 v[40:43], v[32:33], off offset:16
	global_load_dwordx4 v[44:47], v[32:33], off offset:32
	s_mov_b64 s[0:1], 0x800
	v_lshl_add_u64 v[24:25], v[50:51], 0, s[0:1]
	global_load_dwordx4 v[48:51], v[32:33], off offset:48
	s_mov_b64 s[0:1], 0x54b0000
	v_and_b32_e32 v0, 0x3fffff00, v61
	v_lshl_add_u64 v[26:27], v[12:13], 0, s[0:1]
	v_lshl_add_u32 v34, v0, 2, 0
	global_load_dwordx4 v[52:55], v[32:33], off offset:112
	global_load_dwordx4 v[60:63], v[32:33], off offset:96
	global_load_dwordx4 v[64:67], v[32:33], off offset:80
	global_load_dwordx4 v[68:71], v[32:33], off offset:64
	global_load_dwordx4 v[16:19], v[32:33], off offset:176
	global_load_dwordx4 v[72:75], v[32:33], off offset:160
	global_load_dwordx4 v[76:79], v[32:33], off offset:144
	global_load_dwordx4 v[80:83], v[32:33], off offset:128
	global_load_dwordx4 v[0:3], v[32:33], off offset:240
	global_load_dwordx4 v[4:7], v[32:33], off offset:224
	global_load_dwordx4 v[8:11], v[32:33], off offset:208
	global_load_dwordx4 v[12:15], v[32:33], off offset:192
	ds_read_b128 v[84:87], v34
	s_waitcnt vmcnt(15)
	v_lshlrev_b32_e32 v35, 16, v36
	v_and_b32_e32 v56, 0xffff0000, v36
	v_lshlrev_b32_e32 v57, 16, v37
	v_and_b32_e32 v96, 0xffff0000, v37
	v_lshlrev_b32_e32 v97, 16, v38
	v_and_b32_e32 v98, 0xffff0000, v38
	v_lshlrev_b32_e32 v99, 16, v39
	v_and_b32_e32 v100, 0xffff0000, v39
	ds_read_b128 v[36:39], v34 offset:16
	ds_read_b128 v[88:91], v34 offset:32
	ds_read_b128 v[92:95], v34 offset:48
	s_waitcnt lgkmcnt(3)
	v_mul_f32_e32 v56, v85, v56
	v_fmac_f32_e32 v56, v84, v35
	s_waitcnt lgkmcnt(2)
	v_mul_f32_e32 v37, v37, v98
	v_mul_f32_e32 v35, v87, v96
	v_fmac_f32_e32 v37, v36, v97
	v_mul_f32_e32 v36, v39, v100
	v_fmac_f32_e32 v35, v86, v57
	v_fmac_f32_e32 v36, v38, v99
	v_add_f32_e32 v35, v56, v35
	v_add_f32_e32 v36, v37, v36
	s_waitcnt vmcnt(14)
	v_and_b32_e32 v37, 0xffff0000, v40
	v_add_f32_e32 v35, v35, v36
	v_lshlrev_b32_e32 v36, 16, v40
	v_and_b32_e32 v39, 0xffff0000, v41
	s_waitcnt lgkmcnt(1)
	v_mul_f32_e32 v37, v89, v37
	v_lshlrev_b32_e32 v38, 16, v41
	v_fmac_f32_e32 v37, v88, v36
	v_mul_f32_e32 v36, v91, v39
	v_lshlrev_b32_e32 v40, 16, v42
	v_and_b32_e32 v41, 0xffff0000, v42
	v_lshlrev_b32_e32 v42, 16, v43
	v_and_b32_e32 v43, 0xffff0000, v43
	v_fmac_f32_e32 v36, v90, v38
	v_add_f32_e32 v36, v37, v36
	s_waitcnt lgkmcnt(0)
	v_mul_f32_e32 v37, v93, v41
	v_mul_f32_e32 v38, v95, v43
	v_fmac_f32_e32 v37, v92, v40
	v_fmac_f32_e32 v38, v94, v42
	v_add_f32_e32 v37, v37, v38
	v_add_f32_e32 v35, 0, v35
	v_add_f32_e32 v36, v36, v37
	v_add_f32_e32 v35, v35, v36
	ds_read_b128 v[36:39], v34 offset:64
	s_waitcnt vmcnt(13)
	v_and_b32_e32 v40, 0xffff0000, v44
	v_lshlrev_b32_e32 v56, 16, v44
	v_lshlrev_b32_e32 v44, 16, v45
	v_and_b32_e32 v45, 0xffff0000, v45
	s_waitcnt lgkmcnt(0)
; #define LAS __attribute__((address_space(3)))
; __device__ __forceinline__ float dot4(f32x4 a, f32x4 b) { return (a[0] * b[0] + a[1] * b[1]) + (a[2] * b[2] + a[3] * b[3]); }
; __device__ __forceinline__ void unpack8(u32x4 w, f32x4& a, f32x4& b) { a = (f32x4){bflo(w.x), bfhi(w.x), bflo(w.y), bfhi(w.y)}; b = (f32x4){bflo(w.z), bfhi(w.z), bflo(w.w), bfhi(w.w)}; }
; __device__ __forceinline__ void sample_mix_even(Frame& F0, int j, int b) {
;     ...
;         for (int hb = 0; hb < 2; ++hb) {
;             u32x4 pr[16];
; #pragma unroll
;             for (int i = 0; i < 16; ++i) pr[i] = *(const u32x4*)(pm + hb * 128 + i * 8);
; #pragma unroll
;             for (int i = 0; i < 16; ++i) { f32x4 p0, p1; unpack8(pr[i], p0, p1); const LAS float* q = pg + hb * 128 + i * 8; a += dot4(p0, *(const LAS f32x4*)q) + dot4(p1, *(const LAS f32x4*)(q + 4)); }
	v_mul_f32_e32 v37, v37, v40
	ds_read_b128 v[40:43], v34 offset:80
	v_fmac_f32_e32 v37, v36, v56
	v_mul_f32_e32 v36, v39, v45
	v_lshlrev_b32_e32 v57, 16, v46
	v_and_b32_e32 v46, 0xffff0000, v46
	v_lshlrev_b32_e32 v84, 16, v47
	v_and_b32_e32 v47, 0xffff0000, v47
	v_fmac_f32_e32 v36, v38, v44
	v_add_f32_e32 v36, v37, v36
	s_waitcnt lgkmcnt(0)
	v_mul_f32_e32 v37, v41, v46
	v_mul_f32_e32 v38, v43, v47
	v_fmac_f32_e32 v37, v40, v57
	v_fmac_f32_e32 v38, v42, v84
	v_add_f32_e32 v37, v37, v38
	v_add_f32_e32 v36, v36, v37
	v_add_f32_e32 v35, v35, v36
	ds_read_b128 v[36:39], v34 offset:96
	s_waitcnt vmcnt(12)
	v_and_b32_e32 v40, 0xffff0000, v48
	v_lshlrev_b32_e32 v44, 16, v48
	v_and_b32_e32 v46, 0xffff0000, v49
	v_lshlrev_b32_e32 v45, 16, v49
	s_waitcnt lgkmcnt(0)
	v_mul_f32_e32 v37, v37, v40
	ds_read_b128 v[40:43], v34 offset:112
	v_fmac_f32_e32 v37, v36, v44
	v_mul_f32_e32 v36, v39, v46
	v_lshlrev_b32_e32 v47, 16, v50
	v_and_b32_e32 v48, 0xffff0000, v50
	v_and_b32_e32 v50, 0xffff0000, v51
	v_fmac_f32_e32 v36, v38, v45
	v_lshlrev_b32_e32 v49, 16, v51
	v_add_f32_e32 v36, v37, v36
	s_waitcnt lgkmcnt(0)
	v_mul_f32_e32 v37, v41, v48
	v_mul_f32_e32 v38, v43, v50
	v_fmac_f32_e32 v37, v40, v47
	v_fmac_f32_e32 v38, v42, v49
	v_add_f32_e32 v37, v37, v38
	v_add_f32_e32 v36, v36, v37
	v_add_f32_e32 v35, v35, v36
	ds_read_b128 v[36:39], v34 offset:128
	s_waitcnt vmcnt(8)
	v_and_b32_e32 v40, 0xffff0000, v68
	v_lshlrev_b32_e32 v44, 16, v68
	v_and_b32_e32 v46, 0xffff0000, v69
	v_lshlrev_b32_e32 v45, 16, v69
	s_waitcnt lgkmcnt(0)
	v_mul_f32_e32 v37, v37, v40
	ds_read_b128 v[40:43], v34 offset:144
	v_fmac_f32_e32 v37, v36, v44
	v_mul_f32_e32 v36, v39, v46
	v_and_b32_e32 v48, 0xffff0000, v70
	v_and_b32_e32 v50, 0xffff0000, v71
	v_fmac_f32_e32 v36, v38, v45
	v_lshlrev_b32_e32 v47, 16, v70
	v_lshlrev_b32_e32 v49, 16, v71
	v_add_f32_e32 v36, v37, v36
	s_waitcnt lgkmcnt(0)
	v_mul_f32_e32 v37, v41, v48
	v_mul_f32_e32 v38, v43, v50
	v_fmac_f32_e32 v37, v40, v47
	v_fmac_f32_e32 v38, v42, v49
	v_add_f32_e32 v37, v37, v38
	v_add_f32_e32 v36, v36, v37
	v_add_f32_e32 v35, v35, v36
	ds_read_b128 v[36:39], v34 offset:160
	v_and_b32_e32 v40, 0xffff0000, v64
	v_lshlrev_b32_e32 v44, 16, v64
	v_and_b32_e32 v46, 0xffff0000, v65
	v_lshlrev_b32_e32 v45, 16, v65
	s_waitcnt lgkmcnt(0)
	v_mul_f32_e32 v37, v37, v40
	ds_read_b128 v[40:43], v34 offset:176
	v_fmac_f32_e32 v37, v36, v44
	v_mul_f32_e32 v36, v39, v46
	v_and_b32_e32 v48, 0xffff0000, v66
	v_and_b32_e32 v50, 0xffff0000, v67
	v_fmac_f32_e32 v36, v38, v45
	v_lshlrev_b32_e32 v47, 16, v66
	v_lshlrev_b32_e32 v49, 16, v67
	v_add_f32_e32 v36, v37, v36
	s_waitcnt lgkmcnt(0)
	v_mul_f32_e32 v37, v41, v48
	v_mul_f32_e32 v38, v43, v50
	v_fmac_f32_e32 v37, v40, v47
	v_fmac_f32_e32 v38, v42, v49
	v_add_f32_e32 v37, v37, v38
	v_add_f32_e32 v36, v36, v37
	v_add_f32_e32 v35, v35, v36
	ds_read_b128 v[36:39], v34 offset:192
	v_and_b32_e32 v40, 0xffff0000, v60
	v_lshlrev_b32_e32 v44, 16, v60
	v_and_b32_e32 v46, 0xffff0000, v61
	v_lshlrev_b32_e32 v45, 16, v61
	s_waitcnt lgkmcnt(0)
	v_mul_f32_e32 v37, v37, v40
	ds_read_b128 v[40:43], v34 offset:208
	v_fmac_f32_e32 v37, v36, v44
	v_mul_f32_e32 v36, v39, v46
	v_and_b32_e32 v48, 0xffff0000, v62
	v_and_b32_e32 v50, 0xffff0000, v63
	v_fmac_f32_e32 v36, v38, v45
	v_lshlrev_b32_e32 v47, 16, v62
	v_lshlrev_b32_e32 v49, 16, v63
	v_add_f32_e32 v36, v37, v36
	s_waitcnt lgkmcnt(0)
	v_mul_f32_e32 v37, v41, v48
	v_mul_f32_e32 v38, v43, v50
	v_fmac_f32_e32 v37, v40, v47
	v_fmac_f32_e32 v38, v42, v49
	v_add_f32_e32 v37, v37, v38
	v_add_f32_e32 v36, v36, v37
	v_add_f32_e32 v35, v35, v36
	ds_read_b128 v[36:39], v34 offset:224
	v_and_b32_e32 v40, 0xffff0000, v52
	v_lshlrev_b32_e32 v44, 16, v52
	v_and_b32_e32 v46, 0xffff0000, v53
	v_lshlrev_b32_e32 v45, 16, v53
	s_waitcnt lgkmcnt(0)
	v_mul_f32_e32 v37, v37, v40
	ds_read_b128 v[40:43], v34 offset:240
	v_fmac_f32_e32 v37, v36, v44
	v_mul_f32_e32 v36, v39, v46
	v_and_b32_e32 v48, 0xffff0000, v54
	v_and_b32_e32 v50, 0xffff0000, v55
	v_fmac_f32_e32 v36, v38, v45
	v_lshlrev_b32_e32 v47, 16, v54
	v_lshlrev_b32_e32 v49, 16, v55
	v_add_f32_e32 v36, v37, v36
	s_waitcnt lgkmcnt(0)
	v_mul_f32_e32 v37, v41, v48
	v_mul_f32_e32 v38, v43, v50
	v_fmac_f32_e32 v37, v40, v47
	v_fmac_f32_e32 v38, v42, v49
	v_add_f32_e32 v37, v37, v38
	v_add_f32_e32 v36, v36, v37
	v_add_f32_e32 v35, v35, v36
	ds_read_b128 v[36:39], v34 offset:256
	s_waitcnt vmcnt(4)
	v_and_b32_e32 v40, 0xffff0000, v80
	v_lshlrev_b32_e32 v44, 16, v80
	v_and_b32_e32 v46, 0xffff0000, v81
	v_lshlrev_b32_e32 v45, 16, v81
	s_waitcnt lgkmcnt(0)
	v_mul_f32_e32 v37, v37, v40
	ds_read_b128 v[40:43], v34 offset:272
	v_fmac_f32_e32 v37, v36, v44
	v_mul_f32_e32 v36, v39, v46
	v_and_b32_e32 v48, 0xffff0000, v82
	v_and_b32_e32 v50, 0xffff0000, v83
	v_fmac_f32_e32 v36, v38, v45
	v_lshlrev_b32_e32 v47, 16, v82
	v_lshlrev_b32_e32 v49, 16, v83
	v_add_f32_e32 v36, v37, v36
	s_waitcnt lgkmcnt(0)
	v_mul_f32_e32 v37, v41, v48
	v_mul_f32_e32 v38, v43, v50
	v_fmac_f32_e32 v37, v40, v47
	v_fmac_f32_e32 v38, v42, v49
	v_add_f32_e32 v37, v37, v38
	v_add_f32_e32 v36, v36, v37
	v_add_f32_e32 v35, v35, v36
	ds_read_b128 v[36:39], v34 offset:288
	v_and_b32_e32 v40, 0xffff0000, v76
	v_lshlrev_b32_e32 v44, 16, v76
	v_and_b32_e32 v46, 0xffff0000, v77
	v_lshlrev_b32_e32 v45, 16, v77
	s_waitcnt lgkmcnt(0)
	v_mul_f32_e32 v37, v37, v40
	ds_read_b128 v[40:43], v34 offset:304
	v_fmac_f32_e32 v37, v36, v44
	v_mul_f32_e32 v36, v39, v46
	v_and_b32_e32 v48, 0xffff0000, v78
	v_and_b32_e32 v50, 0xffff0000, v79
	v_fmac_f32_e32 v36, v38, v45
	v_lshlrev_b32_e32 v47, 16, v78
	v_lshlrev_b32_e32 v49, 16, v79
	v_add_f32_e32 v36, v37, v36
	s_waitcnt lgkmcnt(0)
; #define LAS __attribute__((address_space(3)))
; __device__ __forceinline__ float silu_f(float x) { return x * __builtin_amdgcn_rcpf(1.f + __builtin_amdgcn_exp2f(-1.4426950408889634f * x)); }
; __device__ __forceinline__ float dot4(f32x4 a, f32x4 b) { return (a[0] * b[0] + a[1] * b[1]) + (a[2] * b[2] + a[3] * b[3]); }
; __device__ __forceinline__ void unpack8(u32x4 w, f32x4& a, f32x4& b) { a = (f32x4){bflo(w.x), bfhi(w.x), bflo(w.y), bfhi(w.y)}; b = (f32x4){bflo(w.z), bfhi(w.z), bflo(w.w), bfhi(w.w)}; }
; __device__ __forceinline__ void sample_mix_even(Frame& F0, int j, int b) {
;     ...
;         for (int hb = 0; hb < 2; ++hb) {
;             u32x4 pr[16];
; #pragma unroll
;             for (int i = 0; i < 16; ++i) pr[i] = *(const u32x4*)(pm + hb * 128 + i * 8);
; #pragma unroll
;             for (int i = 0; i < 16; ++i) { f32x4 p0, p1; unpack8(pr[i], p0, p1); const LAS float* q = pg + hb * 128 + i * 8; a += dot4(p0, *(const LAS f32x4*)q) + dot4(p1, *(const LAS f32x4*)(q + 4)); }
;         }
;         const float ya = a * FIN(12)[j * 1024 + d] * silu_f(z[1024 + d]);
	v_mul_f32_e32 v37, v41, v48
	v_mul_f32_e32 v38, v43, v50
	v_fmac_f32_e32 v37, v40, v47
	v_fmac_f32_e32 v38, v42, v49
	v_add_f32_e32 v37, v37, v38
	v_add_f32_e32 v36, v36, v37
	v_add_f32_e32 v35, v35, v36
	ds_read_b128 v[36:39], v34 offset:320
	v_and_b32_e32 v40, 0xffff0000, v72
	v_lshlrev_b32_e32 v44, 16, v72
	v_and_b32_e32 v46, 0xffff0000, v73
	v_lshlrev_b32_e32 v45, 16, v73
	s_waitcnt lgkmcnt(0)
	v_mul_f32_e32 v37, v37, v40
	ds_read_b128 v[40:43], v34 offset:336
	v_fmac_f32_e32 v37, v36, v44
	v_mul_f32_e32 v36, v39, v46
	v_and_b32_e32 v48, 0xffff0000, v74
	v_and_b32_e32 v50, 0xffff0000, v75
	v_fmac_f32_e32 v36, v38, v45
	v_lshlrev_b32_e32 v47, 16, v74
	v_lshlrev_b32_e32 v49, 16, v75
	v_add_f32_e32 v36, v37, v36
	s_waitcnt lgkmcnt(0)
	v_mul_f32_e32 v37, v41, v48
	v_mul_f32_e32 v38, v43, v50
	v_fmac_f32_e32 v37, v40, v47
	v_fmac_f32_e32 v38, v42, v49
	v_add_f32_e32 v37, v37, v38
	v_add_f32_e32 v36, v36, v37
	v_add_f32_e32 v35, v35, v36
	ds_read_b128 v[36:39], v34 offset:352
	v_lshlrev_b32_e32 v40, 16, v16
	v_and_b32_e32 v16, 0xffff0000, v16
	v_lshlrev_b32_e32 v41, 16, v17
	v_and_b32_e32 v42, 0xffff0000, v17
	v_lshlrev_b32_e32 v43, 16, v18
	v_and_b32_e32 v44, 0xffff0000, v18
	v_lshlrev_b32_e32 v45, 16, v19
	v_and_b32_e32 v46, 0xffff0000, v19
	s_waitcnt lgkmcnt(0)
	v_mul_f32_e32 v37, v37, v16
	ds_read_b128 v[16:19], v34 offset:368
	v_fmac_f32_e32 v37, v36, v40
	v_mul_f32_e32 v36, v39, v42
	v_fmac_f32_e32 v36, v38, v41
	v_add_f32_e32 v36, v37, v36
	s_waitcnt lgkmcnt(0)
	v_mul_f32_e32 v17, v17, v44
	v_fmac_f32_e32 v17, v16, v43
	v_mul_f32_e32 v16, v19, v46
	v_fmac_f32_e32 v16, v18, v45
	v_add_f32_e32 v16, v17, v16
	v_add_f32_e32 v16, v36, v16
	v_add_f32_e32 v35, v35, v16
	ds_read_b128 v[16:19], v34 offset:384
	s_waitcnt vmcnt(0)
	v_lshlrev_b32_e32 v36, 16, v12
	v_and_b32_e32 v12, 0xffff0000, v12
	v_lshlrev_b32_e32 v37, 16, v13
	v_and_b32_e32 v38, 0xffff0000, v13
	v_lshlrev_b32_e32 v39, 16, v14
	v_and_b32_e32 v40, 0xffff0000, v14
	v_lshlrev_b32_e32 v41, 16, v15
	v_and_b32_e32 v42, 0xffff0000, v15
	s_waitcnt lgkmcnt(0)
	v_mul_f32_e32 v17, v17, v12
	ds_read_b128 v[12:15], v34 offset:400
	v_fmac_f32_e32 v17, v16, v36
	v_mul_f32_e32 v16, v19, v38
	v_fmac_f32_e32 v16, v18, v37
	v_add_f32_e32 v16, v17, v16
	s_waitcnt lgkmcnt(0)
	v_mul_f32_e32 v13, v13, v40
	v_fmac_f32_e32 v13, v12, v39
	v_mul_f32_e32 v12, v15, v42
	v_fmac_f32_e32 v12, v14, v41
	v_add_f32_e32 v12, v13, v12
	v_add_f32_e32 v12, v16, v12
	v_add_f32_e32 v16, v35, v12
	ds_read_b128 v[12:15], v34 offset:416
	global_load_dwordx4 v[36:39], v[32:33], off offset:256
	v_lshlrev_b32_e32 v17, 16, v8
	v_and_b32_e32 v8, 0xffff0000, v8
	v_lshlrev_b32_e32 v18, 16, v9
	v_and_b32_e32 v19, 0xffff0000, v9
	v_lshlrev_b32_e32 v35, 16, v10
	v_and_b32_e32 v40, 0xffff0000, v10
	v_lshlrev_b32_e32 v41, 16, v11
	v_and_b32_e32 v42, 0xffff0000, v11
	s_waitcnt lgkmcnt(0)
	v_mul_f32_e32 v13, v13, v8
	ds_read_b128 v[8:11], v34 offset:432
	v_fmac_f32_e32 v13, v12, v17
	v_mul_f32_e32 v12, v15, v19
	v_fmac_f32_e32 v12, v14, v18
	v_add_f32_e32 v12, v13, v12
	s_waitcnt lgkmcnt(0)
	v_mul_f32_e32 v9, v9, v40
	v_fmac_f32_e32 v9, v8, v35
	v_mul_f32_e32 v8, v11, v42
	v_fmac_f32_e32 v8, v10, v41
	global_load_dwordx4 v[40:43], v[32:33], off offset:272
	v_add_f32_e32 v8, v9, v8
	v_add_f32_e32 v8, v12, v8
	v_add_f32_e32 v12, v16, v8
	ds_read_b128 v[8:11], v34 offset:448
	global_load_dwordx4 v[44:47], v[32:33], off offset:288
	v_lshlrev_b32_e32 v13, 16, v4
	v_and_b32_e32 v4, 0xffff0000, v4
	v_lshlrev_b32_e32 v14, 16, v5
	v_and_b32_e32 v15, 0xffff0000, v5
	v_lshlrev_b32_e32 v16, 16, v6
	v_and_b32_e32 v17, 0xffff0000, v6
	v_lshlrev_b32_e32 v18, 16, v7
	v_and_b32_e32 v19, 0xffff0000, v7
	s_waitcnt lgkmcnt(0)
	v_mul_f32_e32 v9, v9, v4
	ds_read_b128 v[4:7], v34 offset:464
	v_fmac_f32_e32 v9, v8, v13
	v_mul_f32_e32 v8, v11, v15
	v_fmac_f32_e32 v8, v10, v14
	global_load_dwordx4 v[48:51], v[32:33], off offset:304
	s_waitcnt lgkmcnt(0)
	v_mul_f32_e32 v5, v5, v17
	v_fmac_f32_e32 v5, v4, v16
	v_mul_f32_e32 v4, v7, v19
	v_fmac_f32_e32 v4, v6, v18
	v_add_f32_e32 v8, v9, v8
	v_add_f32_e32 v4, v5, v4
	v_add_f32_e32 v4, v8, v4
	v_add_f32_e32 v8, v12, v4
	ds_read_b128 v[4:7], v34 offset:480
	v_lshlrev_b32_e32 v9, 16, v0
	v_and_b32_e32 v0, 0xffff0000, v0
	v_lshlrev_b32_e32 v10, 16, v1
	v_and_b32_e32 v11, 0xffff0000, v1
	v_lshlrev_b32_e32 v12, 16, v2
	v_and_b32_e32 v13, 0xffff0000, v2
	v_lshlrev_b32_e32 v14, 16, v3
	v_and_b32_e32 v15, 0xffff0000, v3
	s_waitcnt lgkmcnt(0)
	v_mul_f32_e32 v5, v5, v0
	ds_read_b128 v[0:3], v34 offset:496
	v_fmac_f32_e32 v5, v4, v9
	v_mul_f32_e32 v4, v7, v11
	v_fmac_f32_e32 v4, v6, v10
	v_add_f32_e32 v4, v5, v4
	s_waitcnt lgkmcnt(0)
	v_mul_f32_e32 v1, v1, v13
	v_fmac_f32_e32 v1, v0, v12
	v_mul_f32_e32 v0, v3, v15
	v_fmac_f32_e32 v0, v2, v14
	v_add_f32_e32 v0, v1, v0
	v_add_f32_e32 v0, v4, v0
	v_add_f32_e32 v35, v8, v0
	global_load_dwordx4 v[52:55], v[32:33], off offset:368
	global_load_dwordx4 v[60:63], v[32:33], off offset:352
	global_load_dwordx4 v[64:67], v[32:33], off offset:336
	global_load_dwordx4 v[68:71], v[32:33], off offset:320
	global_load_dwordx4 v[16:19], v[32:33], off offset:432
	global_load_dwordx4 v[72:75], v[32:33], off offset:416
	global_load_dwordx4 v[76:79], v[32:33], off offset:400
	global_load_dwordx4 v[80:83], v[32:33], off offset:384
	global_load_dwordx4 v[0:3], v[32:33], off offset:496
	global_load_dwordx4 v[4:7], v[32:33], off offset:480
	global_load_dwordx4 v[8:11], v[32:33], off offset:464
	global_load_dwordx4 v[12:15], v[32:33], off offset:448
	ds_read_b128 v[84:87], v34 offset:512
	global_load_dword v28, v[28:29], off offset:2048
	s_waitcnt vmcnt(16)
; #define LAS __attribute__((address_space(3)))
; __device__ __forceinline__ float dot4(f32x4 a, f32x4 b) { return (a[0] * b[0] + a[1] * b[1]) + (a[2] * b[2] + a[3] * b[3]); }
; __device__ __forceinline__ void unpack8(u32x4 w, f32x4& a, f32x4& b) { a = (f32x4){bflo(w.x), bfhi(w.x), bflo(w.y), bfhi(w.y)}; b = (f32x4){bflo(w.z), bfhi(w.z), bflo(w.w), bfhi(w.w)}; }
; __device__ __forceinline__ void sample_mix_even(Frame& F0, int j, int b) {
;     ...
;         for (int hb = 0; hb < 2; ++hb) {
;             u32x4 pr[16];
; #pragma unroll
;             for (int i = 0; i < 16; ++i) pr[i] = *(const u32x4*)(pm + hb * 128 + i * 8);
; #pragma unroll
;             for (int i = 0; i < 16; ++i) { f32x4 p0, p1; unpack8(pr[i], p0, p1); const LAS float* q = pg + hb * 128 + i * 8; a += dot4(p0, *(const LAS f32x4*)q) + dot4(p1, *(const LAS f32x4*)(q + 4)); }
	v_lshlrev_b32_e32 v32, 16, v36
	v_and_b32_e32 v33, 0xffff0000, v36
	v_lshlrev_b32_e32 v56, 16, v37
	v_and_b32_e32 v57, 0xffff0000, v37
	v_lshlrev_b32_e32 v88, 16, v38
	v_and_b32_e32 v89, 0xffff0000, v38
	v_lshlrev_b32_e32 v90, 16, v39
	v_and_b32_e32 v91, 0xffff0000, v39
	ds_read_b128 v[36:39], v34 offset:528
	s_waitcnt lgkmcnt(1)
	v_mul_f32_e32 v33, v85, v33
	v_fmac_f32_e32 v33, v84, v32
	v_mul_f32_e32 v32, v87, v57
	v_fmac_f32_e32 v32, v86, v56
	v_add_f32_e32 v32, v33, v32
	s_waitcnt lgkmcnt(0)
	v_mul_f32_e32 v33, v37, v89
	v_fmac_f32_e32 v33, v36, v88
	v_mul_f32_e32 v36, v39, v91
	v_fmac_f32_e32 v36, v38, v90
	v_add_f32_e32 v33, v33, v36
	ds_read_b128 v[36:39], v34 offset:544
	v_add_f32_e32 v32, v32, v33
	v_add_f32_e32 v32, v35, v32
	s_waitcnt vmcnt(15)
	v_lshlrev_b32_e32 v33, 16, v40
	v_and_b32_e32 v35, 0xffff0000, v40
	v_lshlrev_b32_e32 v56, 16, v41
	v_and_b32_e32 v57, 0xffff0000, v41
	v_lshlrev_b32_e32 v84, 16, v42
	v_and_b32_e32 v85, 0xffff0000, v42
	v_lshlrev_b32_e32 v86, 16, v43
	v_and_b32_e32 v87, 0xffff0000, v43
	ds_read_b128 v[40:43], v34 offset:560
	s_waitcnt lgkmcnt(1)
	v_mul_f32_e32 v35, v37, v35
	v_fmac_f32_e32 v35, v36, v33
	v_mul_f32_e32 v33, v39, v57
	v_fmac_f32_e32 v33, v38, v56
	v_add_f32_e32 v33, v35, v33
	s_waitcnt lgkmcnt(0)
	v_mul_f32_e32 v35, v41, v85
	v_mul_f32_e32 v36, v43, v87
	v_fmac_f32_e32 v35, v40, v84
	v_fmac_f32_e32 v36, v42, v86
	v_add_f32_e32 v35, v35, v36
	ds_read_b128 v[36:39], v34 offset:576
	ds_read_b128 v[40:43], v34 offset:592
	v_add_f32_e32 v33, v33, v35
	s_waitcnt vmcnt(14)
	v_and_b32_e32 v35, 0xffff0000, v44
	v_add_f32_e32 v32, v32, v33
	v_lshlrev_b32_e32 v33, 16, v44
	v_lshlrev_b32_e32 v44, 16, v45
	v_and_b32_e32 v45, 0xffff0000, v45
	s_waitcnt lgkmcnt(1)
	v_mul_f32_e32 v35, v37, v35
	v_fmac_f32_e32 v35, v36, v33
	v_mul_f32_e32 v33, v39, v45
	v_lshlrev_b32_e32 v56, 16, v46
	v_and_b32_e32 v46, 0xffff0000, v46
	v_lshlrev_b32_e32 v57, 16, v47
	v_and_b32_e32 v47, 0xffff0000, v47
	v_fmac_f32_e32 v33, v38, v44
	v_add_f32_e32 v33, v35, v33
	s_waitcnt lgkmcnt(0)
	v_mul_f32_e32 v35, v41, v46
	v_mul_f32_e32 v36, v43, v47
	v_fmac_f32_e32 v35, v40, v56
	v_fmac_f32_e32 v36, v42, v57
	v_add_f32_e32 v35, v35, v36
	ds_read_b128 v[36:39], v34 offset:608
	ds_read_b128 v[40:43], v34 offset:624
	v_add_f32_e32 v33, v33, v35
	s_waitcnt vmcnt(13)
	v_and_b32_e32 v35, 0xffff0000, v48
	v_add_f32_e32 v32, v32, v33
	v_lshlrev_b32_e32 v33, 16, v48
	v_and_b32_e32 v45, 0xffff0000, v49
	s_waitcnt lgkmcnt(1)
	v_mul_f32_e32 v35, v37, v35
	v_lshlrev_b32_e32 v44, 16, v49
	v_fmac_f32_e32 v35, v36, v33
	v_mul_f32_e32 v33, v39, v45
	v_and_b32_e32 v47, 0xffff0000, v50
	v_and_b32_e32 v49, 0xffff0000, v51
	v_fmac_f32_e32 v33, v38, v44
	v_lshlrev_b32_e32 v46, 16, v50
	v_lshlrev_b32_e32 v48, 16, v51
	v_add_f32_e32 v33, v35, v33
	s_waitcnt lgkmcnt(0)
	v_mul_f32_e32 v35, v41, v47
	v_mul_f32_e32 v36, v43, v49
	v_fmac_f32_e32 v35, v40, v46
	v_fmac_f32_e32 v36, v42, v48
	v_add_f32_e32 v35, v35, v36
	ds_read_b128 v[36:39], v34 offset:640
	ds_read_b128 v[40:43], v34 offset:656
	v_add_f32_e32 v33, v33, v35
	s_waitcnt vmcnt(9)
	v_and_b32_e32 v35, 0xffff0000, v68
	v_add_f32_e32 v32, v32, v33
	v_lshlrev_b32_e32 v33, 16, v68
	v_and_b32_e32 v45, 0xffff0000, v69
	s_waitcnt lgkmcnt(1)
	v_mul_f32_e32 v35, v37, v35
	v_lshlrev_b32_e32 v44, 16, v69
	v_fmac_f32_e32 v35, v36, v33
	v_mul_f32_e32 v33, v39, v45
	v_and_b32_e32 v47, 0xffff0000, v70
	v_and_b32_e32 v49, 0xffff0000, v71
	v_fmac_f32_e32 v33, v38, v44
	v_lshlrev_b32_e32 v46, 16, v70
	v_lshlrev_b32_e32 v48, 16, v71
	v_add_f32_e32 v33, v35, v33
	s_waitcnt lgkmcnt(0)
	v_mul_f32_e32 v35, v41, v47
	v_mul_f32_e32 v36, v43, v49
	v_fmac_f32_e32 v35, v40, v46
	v_fmac_f32_e32 v36, v42, v48
	v_add_f32_e32 v35, v35, v36
	ds_read_b128 v[36:39], v34 offset:672
	ds_read_b128 v[40:43], v34 offset:688
	v_add_f32_e32 v33, v33, v35
	v_and_b32_e32 v35, 0xffff0000, v64
	v_add_f32_e32 v32, v32, v33
	v_lshlrev_b32_e32 v33, 16, v64
	v_and_b32_e32 v45, 0xffff0000, v65
	s_waitcnt lgkmcnt(1)
	v_mul_f32_e32 v35, v37, v35
	v_lshlrev_b32_e32 v44, 16, v65
	v_fmac_f32_e32 v35, v36, v33
	v_mul_f32_e32 v33, v39, v45
	v_and_b32_e32 v47, 0xffff0000, v66
	v_and_b32_e32 v49, 0xffff0000, v67
	v_fmac_f32_e32 v33, v38, v44
	v_lshlrev_b32_e32 v46, 16, v66
	v_lshlrev_b32_e32 v48, 16, v67
	v_add_f32_e32 v33, v35, v33
	s_waitcnt lgkmcnt(0)
	v_mul_f32_e32 v35, v41, v47
	v_mul_f32_e32 v36, v43, v49
	v_fmac_f32_e32 v35, v40, v46
	v_fmac_f32_e32 v36, v42, v48
	v_add_f32_e32 v35, v35, v36
	ds_read_b128 v[36:39], v34 offset:704
	ds_read_b128 v[40:43], v34 offset:720
	v_add_f32_e32 v33, v33, v35
	v_and_b32_e32 v35, 0xffff0000, v60
	v_add_f32_e32 v32, v32, v33
	v_lshlrev_b32_e32 v33, 16, v60
	v_and_b32_e32 v45, 0xffff0000, v61
	s_waitcnt lgkmcnt(1)
	v_mul_f32_e32 v35, v37, v35
	v_lshlrev_b32_e32 v44, 16, v61
	v_fmac_f32_e32 v35, v36, v33
	v_mul_f32_e32 v33, v39, v45
	v_and_b32_e32 v47, 0xffff0000, v62
	v_and_b32_e32 v49, 0xffff0000, v63
	v_fmac_f32_e32 v33, v38, v44
	v_lshlrev_b32_e32 v46, 16, v62
	v_lshlrev_b32_e32 v48, 16, v63
	v_add_f32_e32 v33, v35, v33
	s_waitcnt lgkmcnt(0)
	v_mul_f32_e32 v35, v41, v47
	v_mul_f32_e32 v36, v43, v49
	v_fmac_f32_e32 v35, v40, v46
	v_fmac_f32_e32 v36, v42, v48
	v_add_f32_e32 v35, v35, v36
	ds_read_b128 v[36:39], v34 offset:736
	ds_read_b128 v[40:43], v34 offset:752
	v_add_f32_e32 v33, v33, v35
	v_and_b32_e32 v35, 0xffff0000, v52
	v_add_f32_e32 v32, v32, v33
	v_lshlrev_b32_e32 v33, 16, v52
	v_and_b32_e32 v45, 0xffff0000, v53
	s_waitcnt lgkmcnt(1)
	v_mul_f32_e32 v35, v37, v35
	v_lshlrev_b32_e32 v44, 16, v53
	v_fmac_f32_e32 v35, v36, v33
	v_mul_f32_e32 v33, v39, v45
	v_and_b32_e32 v47, 0xffff0000, v54
	v_and_b32_e32 v49, 0xffff0000, v55
	v_fmac_f32_e32 v33, v38, v44
	v_lshlrev_b32_e32 v46, 16, v54
	v_lshlrev_b32_e32 v48, 16, v55
	v_add_f32_e32 v33, v35, v33
	s_waitcnt lgkmcnt(0)
; #define LAS __attribute__((address_space(3)))
; __device__ __forceinline__ float dot4(f32x4 a, f32x4 b) { return (a[0] * b[0] + a[1] * b[1]) + (a[2] * b[2] + a[3] * b[3]); }
; __device__ __forceinline__ void unpack8(u32x4 w, f32x4& a, f32x4& b) { a = (f32x4){bflo(w.x), bfhi(w.x), bflo(w.y), bfhi(w.y)}; b = (f32x4){bflo(w.z), bfhi(w.z), bflo(w.w), bfhi(w.w)}; }
; __device__ __forceinline__ void sample_mix_even(Frame& F0, int j, int b) {
;     ...
;         for (int hb = 0; hb < 2; ++hb) {
;             u32x4 pr[16];
; #pragma unroll
;             for (int i = 0; i < 16; ++i) pr[i] = *(const u32x4*)(pm + hb * 128 + i * 8);
; #pragma unroll
;             for (int i = 0; i < 16; ++i) { f32x4 p0, p1; unpack8(pr[i], p0, p1); const LAS float* q = pg + hb * 128 + i * 8; a += dot4(p0, *(const LAS f32x4*)q) + dot4(p1, *(const LAS f32x4*)(q + 4)); }
	v_mul_f32_e32 v35, v41, v47
	v_mul_f32_e32 v36, v43, v49
	v_fmac_f32_e32 v35, v40, v46
	v_fmac_f32_e32 v36, v42, v48
	v_add_f32_e32 v35, v35, v36
	ds_read_b128 v[36:39], v34 offset:768
	ds_read_b128 v[40:43], v34 offset:784
	v_add_f32_e32 v33, v33, v35
	s_waitcnt vmcnt(5)
	v_and_b32_e32 v35, 0xffff0000, v80
	v_add_f32_e32 v32, v32, v33
	v_lshlrev_b32_e32 v33, 16, v80
	v_and_b32_e32 v45, 0xffff0000, v81
	s_waitcnt lgkmcnt(1)
	v_mul_f32_e32 v35, v37, v35
	v_lshlrev_b32_e32 v44, 16, v81
	v_fmac_f32_e32 v35, v36, v33
	v_mul_f32_e32 v33, v39, v45
	v_and_b32_e32 v47, 0xffff0000, v82
	v_and_b32_e32 v49, 0xffff0000, v83
	v_fmac_f32_e32 v33, v38, v44
	v_lshlrev_b32_e32 v46, 16, v82
	v_lshlrev_b32_e32 v48, 16, v83
	v_add_f32_e32 v33, v35, v33
	s_waitcnt lgkmcnt(0)
	v_mul_f32_e32 v35, v41, v47
	v_mul_f32_e32 v36, v43, v49
	v_fmac_f32_e32 v35, v40, v46
	v_fmac_f32_e32 v36, v42, v48
	v_add_f32_e32 v35, v35, v36
	ds_read_b128 v[36:39], v34 offset:800
	ds_read_b128 v[40:43], v34 offset:816
	v_add_f32_e32 v33, v33, v35
	v_and_b32_e32 v35, 0xffff0000, v76
	v_add_f32_e32 v32, v32, v33
	v_lshlrev_b32_e32 v33, 16, v76
	v_and_b32_e32 v45, 0xffff0000, v77
	s_waitcnt lgkmcnt(1)
	v_mul_f32_e32 v35, v37, v35
	v_lshlrev_b32_e32 v44, 16, v77
	v_fmac_f32_e32 v35, v36, v33
	v_mul_f32_e32 v33, v39, v45
	v_and_b32_e32 v47, 0xffff0000, v78
	v_and_b32_e32 v49, 0xffff0000, v79
	v_fmac_f32_e32 v33, v38, v44
	ds_read_b128 v[36:39], v34 offset:832
	v_lshlrev_b32_e32 v46, 16, v78
	v_lshlrev_b32_e32 v48, 16, v79
	v_add_f32_e32 v29, v35, v33
	s_waitcnt lgkmcnt(1)
	v_mul_f32_e32 v33, v41, v47
	v_mul_f32_e32 v35, v43, v49
	v_fmac_f32_e32 v33, v40, v46
	v_fmac_f32_e32 v35, v42, v48
	v_add_f32_e32 v33, v33, v35
	ds_read_b128 v[40:43], v34 offset:848
	v_add_f32_e32 v29, v29, v33
	v_and_b32_e32 v33, 0xffff0000, v72
	v_add_f32_e32 v29, v32, v29
	v_lshlrev_b32_e32 v32, 16, v72
	v_and_b32_e32 v44, 0xffff0000, v73
	s_waitcnt lgkmcnt(1)
	v_mul_f32_e32 v33, v37, v33
	v_lshlrev_b32_e32 v35, 16, v73
	v_fmac_f32_e32 v33, v36, v32
	v_mul_f32_e32 v32, v39, v44
	v_and_b32_e32 v46, 0xffff0000, v74
	v_and_b32_e32 v48, 0xffff0000, v75
	v_fmac_f32_e32 v32, v38, v35
	v_lshlrev_b32_e32 v45, 16, v74
	v_lshlrev_b32_e32 v47, 16, v75
	v_add_f32_e32 v32, v33, v32
	s_waitcnt lgkmcnt(0)
	v_mul_f32_e32 v33, v41, v46
	v_mul_f32_e32 v35, v43, v48
	ds_read_b128 v[36:39], v34 offset:864
	v_fmac_f32_e32 v33, v40, v45
	v_fmac_f32_e32 v35, v42, v47
	v_add_f32_e32 v33, v33, v35
	v_add_f32_e32 v32, v32, v33
	v_add_f32_e32 v29, v29, v32
	v_lshlrev_b32_e32 v32, 16, v16
	v_and_b32_e32 v16, 0xffff0000, v16
	v_lshlrev_b32_e32 v33, 16, v17
	v_and_b32_e32 v35, 0xffff0000, v17
	v_lshlrev_b32_e32 v40, 16, v18
	v_and_b32_e32 v41, 0xffff0000, v18
	v_lshlrev_b32_e32 v42, 16, v19
	v_and_b32_e32 v43, 0xffff0000, v19
	s_waitcnt lgkmcnt(0)
	v_mul_f32_e32 v37, v37, v16
	ds_read_b128 v[16:19], v34 offset:880
	v_fmac_f32_e32 v37, v36, v32
	v_mul_f32_e32 v32, v39, v35
	v_fmac_f32_e32 v32, v38, v33
	v_add_f32_e32 v32, v37, v32
	s_waitcnt lgkmcnt(0)
	v_mul_f32_e32 v17, v17, v41
	ds_read_b128 v[36:39], v34 offset:896
	v_fmac_f32_e32 v17, v16, v40
	v_mul_f32_e32 v16, v19, v43
	v_fmac_f32_e32 v16, v18, v42
	ds_read_b128 v[40:43], v34 offset:912
	v_add_f32_e32 v16, v17, v16
	s_waitcnt vmcnt(1)
	v_lshlrev_b32_e32 v17, 16, v12
	v_and_b32_e32 v12, 0xffff0000, v12
	v_lshlrev_b32_e32 v18, 16, v13
	v_and_b32_e32 v13, 0xffff0000, v13
	s_waitcnt lgkmcnt(1)
	v_mul_f32_e32 v12, v37, v12
	v_mul_f32_e32 v13, v39, v13
	v_add_f32_e32 v16, v32, v16
	v_lshlrev_b32_e32 v19, 16, v14
	v_and_b32_e32 v14, 0xffff0000, v14
	v_and_b32_e32 v32, 0xffff0000, v15
	v_fmac_f32_e32 v12, v36, v17
	v_fmac_f32_e32 v13, v38, v18
	v_add_f32_e32 v16, v29, v16
	v_lshlrev_b32_e32 v29, 16, v15
	v_add_f32_e32 v15, v12, v13
	s_waitcnt lgkmcnt(0)
; __device__ __forceinline__ unsigned cvt_pk_bf16(float lo, float hi) { const f32x2cv v = {lo, hi}; return __builtin_bit_cast(unsigned, __builtin_convertvector(v, bf16x2cv)); }
; #define LAS __attribute__((address_space(3)))
; __device__ __forceinline__ float silu_f(float x) { return x * __builtin_amdgcn_rcpf(1.f + __builtin_amdgcn_exp2f(-1.4426950408889634f * x)); }
; __device__ __forceinline__ float dot4(f32x4 a, f32x4 b) { return (a[0] * b[0] + a[1] * b[1]) + (a[2] * b[2] + a[3] * b[3]); }
; __device__ __forceinline__ void unpack8(u32x4 w, f32x4& a, f32x4& b) { a = (f32x4){bflo(w.x), bfhi(w.x), bflo(w.y), bfhi(w.y)}; b = (f32x4){bflo(w.z), bfhi(w.z), bflo(w.w), bfhi(w.w)}; }
; __device__ __forceinline__ void sample_mix_even(Frame& F0, int j, int b) {
;     ...
;             for (int i = 0; i < 16; ++i) { f32x4 p0, p1; unpack8(pr[i], p0, p1); const LAS float* q = pg + hb * 128 + i * 8; a += dot4(p0, *(const LAS f32x4*)q) + dot4(p1, *(const LAS f32x4*)(q + 4)); }
;         }
;         const float ya = a * FIN(12)[j * 1024 + d] * silu_f(z[1024 + d]);
;         const float vn = vv[k] * rv * FIN(15)[j * 1024 + d];
;         F.out[O_SGUV + (size_t)(j * 128 + b) * 1024 + d] = vn;
;         const float mixed = FIN(13)[(size_t)(j * 4 + g) * 16384] * vn + FIN(14)[(j * 4 + g) * 128];
;         const float yb = z[2048 + d] * mixed * silu_f(z[4096 + d]);
;         ((bf16_t*)(F.ws + WS_SA2))[(size_t)b * 2048 + d] = (bf16_t)(cvt_pk_bf16(ya, 0.f) & 0xffffu); ((bf16_t*)(F.ws + WS_SA2))[(size_t)b * 2048 + 1024 + d] = (bf16_t)(cvt_pk_bf16(yb, 0.f) & 0xffffu);
;     }
	v_mul_f32_e32 v12, v41, v14
	v_mul_f32_e32 v13, v43, v32
	v_fmac_f32_e32 v12, v40, v19
	v_fmac_f32_e32 v13, v42, v29
	v_add_f32_e32 v17, v12, v13
	v_add_co_u32_e32 v12, vcc, s70, v24
	v_mul_f32_e32 v19, v58, v59
	s_nop 0
	v_addc_co_u32_e32 v13, vcc, 0, v25, vcc
	s_waitcnt vmcnt(0)
	v_mul_f32_e32 v19, v19, v28
	v_add_co_u32_e32 v24, vcc, s94, v24
	global_load_dword v14, v[30:31], off offset:2048
	global_load_dword v18, v[12:13], off offset:-4096
	v_addc_co_u32_e32 v25, vcc, 0, v25, vcc
	global_store_dword v[26:27], v19, off offset:2048
	global_load_dword v26, v[24:25], off
	v_lshlrev_b64 v[24:25], 16, v[22:23]
	v_lshlrev_b32_e32 v22, 7, v22
	v_lshl_add_u64 v[24:25], s[6:7], 0, v[24:25]
	v_ashrrev_i32_e32 v23, 31, v22
	v_add_f32_e32 v15, v15, v17
	global_load_dword v17, v[24:25], off
	v_lshl_add_u64 v[22:23], v[22:23], 2, s[8:9]
	global_load_dword v27, v[22:23], off
	s_nop 0
	global_load_dword v12, v[12:13], off
	ds_read_b128 v[22:25], v34 offset:928
	v_add_f32_e32 v13, v16, v15
	v_lshlrev_b32_e32 v15, 16, v8
	v_and_b32_e32 v8, 0xffff0000, v8
	v_lshlrev_b32_e32 v16, 16, v9
	v_and_b32_e32 v28, 0xffff0000, v9
	v_lshlrev_b32_e32 v29, 16, v10
	v_and_b32_e32 v30, 0xffff0000, v10
	v_lshlrev_b32_e32 v31, 16, v11
	v_and_b32_e32 v32, 0xffff0000, v11
	s_waitcnt lgkmcnt(0)
	v_mul_f32_e32 v23, v23, v8
	ds_read_b128 v[8:11], v34 offset:944
	v_fmac_f32_e32 v23, v22, v15
	v_mul_f32_e32 v15, v25, v28
	v_fmac_f32_e32 v15, v24, v16
	v_add_f32_e32 v15, v23, v15
	s_waitcnt lgkmcnt(0)
	v_mul_f32_e32 v9, v9, v30
	v_fmac_f32_e32 v9, v8, v29
	v_mul_f32_e32 v8, v11, v32
	v_fmac_f32_e32 v8, v10, v31
	v_add_f32_e32 v8, v9, v8
	v_add_f32_e32 v8, v15, v8
	v_add_f32_e32 v13, v13, v8
	ds_read_b128 v[8:11], v34 offset:960
	v_lshlrev_b32_e32 v15, 16, v4
	v_and_b32_e32 v4, 0xffff0000, v4
	v_lshlrev_b32_e32 v16, 16, v5
	v_and_b32_e32 v22, 0xffff0000, v5
	v_lshlrev_b32_e32 v23, 16, v6
	v_and_b32_e32 v24, 0xffff0000, v6
	v_lshlrev_b32_e32 v25, 16, v7
	v_and_b32_e32 v28, 0xffff0000, v7
	s_waitcnt lgkmcnt(0)
	v_mul_f32_e32 v9, v9, v4
	ds_read_b128 v[4:7], v34 offset:976
	v_fmac_f32_e32 v9, v8, v15
	v_mul_f32_e32 v8, v11, v22
	v_fmac_f32_e32 v8, v10, v16
	v_add_f32_e32 v8, v9, v8
	s_waitcnt lgkmcnt(0)
	v_mul_f32_e32 v5, v5, v24
	v_fmac_f32_e32 v5, v4, v23
	v_mul_f32_e32 v4, v7, v28
	v_fmac_f32_e32 v4, v6, v25
	v_add_f32_e32 v4, v5, v4
	v_add_f32_e32 v4, v8, v4
	v_add_f32_e32 v8, v13, v4
	ds_read_b128 v[4:7], v34 offset:992
	v_lshlrev_b32_e32 v9, 16, v0
	v_and_b32_e32 v0, 0xffff0000, v0
	v_lshlrev_b32_e32 v10, 16, v1
	v_and_b32_e32 v11, 0xffff0000, v1
	v_lshlrev_b32_e32 v13, 16, v2
	v_and_b32_e32 v15, 0xffff0000, v2
	v_lshlrev_b32_e32 v16, 16, v3
	v_and_b32_e32 v22, 0xffff0000, v3
	s_waitcnt lgkmcnt(0)
	v_mul_f32_e32 v5, v5, v0
	ds_read_b128 v[0:3], v34 offset:1008
	v_fmac_f32_e32 v5, v4, v9
	v_mul_f32_e32 v4, v7, v11
	v_fmac_f32_e32 v4, v6, v10
	v_add_f32_e32 v4, v5, v4
	s_waitcnt lgkmcnt(0)
	v_mul_f32_e32 v1, v1, v15
	v_fmac_f32_e32 v1, v0, v13
	v_mul_f32_e32 v0, v3, v22
	v_fmac_f32_e32 v0, v2, v16
	v_add_f32_e32 v0, v1, v0
	v_add_f32_e32 v0, v4, v0
	v_add_f32_e32 v0, v8, v0
	s_waitcnt vmcnt(5)
	v_mul_f32_e32 v3, 0xbfb8aa3b, v18
	v_exp_f32_e32 v3, v3
	v_mul_f32_e32 v0, v14, v0
	s_waitcnt vmcnt(3)
	v_mul_f32_e32 v2, 0xbfb8aa3b, v26
	v_exp_f32_e32 v2, v2
	v_add_f32_e32 v1, 1.0, v3
	v_rcp_f32_e32 v1, v1
	v_add_f32_e32 v2, 1.0, v2
	v_rcp_f32_e32 v2, v2
	v_mul_f32_e32 v1, v18, v1
	s_waitcnt vmcnt(1)
	v_fmac_f32_e32 v27, v19, v17
	v_mul_f32_e32 v0, v0, v1
	s_waitcnt vmcnt(0)
	v_mul_f32_e32 v1, v12, v27
	v_mul_f32_e32 v2, v26, v2
	v_mul_f32_e32 v1, v1, v2
	v_cvt_pk_bf16_f32 v0, v0, s0
	global_store_short v[20:21], v0, off offset:1024
	v_cvt_pk_bf16_f32 v0, v1, s0
	global_store_short v[20:21], v0, off offset:3072
